# gate/up epilogue: packed v_pk_mul_f32 split into two v_mul_f32 each
# baseline (speedup 1.0000x reference)
.LBB0_377:
	s_and_b64 vcc, exec, s[42:43]
	s_cbranch_vccz .LBB0_376
	v_readlane_b32 s48, v233, 52
	v_readlane_b32 s49, v233, 53
	s_andn2_b64 vcc, exec, s[48:49]
	s_nop 0
	v_cndmask_b32_e64 v141, 0, 1, s[48:49]
	v_cmp_ne_u32_e64 s[42:43], 1, v141
	s_cbranch_vccnz .LBB0_380
	v_mul_f32_e32 v141, 0xbfb8aa3b, v126
	v_exp_f32_e32 v141, v141
	s_nop 0
	v_add_f32_e32 v141, 1.0, v141
	s_waitcnt lgkmcnt(0)
	v_rcp_f32_e32 v142, v141
	v_mul_f32_e32 v141, 0xbfb8aa3b, v122
	v_exp_f32_e32 v141, v141
	s_nop 0
	v_add_f32_e32 v141, 1.0, v141
	v_rcp_f32_e32 v144, v141
	v_mul_f32_e32 v141, 0xbfb8aa3b, v127
	v_exp_f32_e32 v141, v141
	s_nop 0
	v_add_f32_e32 v141, 1.0, v141
	v_rcp_f32_e32 v143, v141
	v_mul_f32_e32 v141, 0xbfb8aa3b, v123
	v_exp_f32_e32 v141, v141
	v_mul_f32_e32 v126, v126, v142
	v_mul_f32_e32 v127, v127, v143
	v_add_f32_e32 v141, 1.0, v141
	v_rcp_f32_e32 v145, v141
	v_mul_f32_e32 v141, 0xbfb8aa3b, v128
	v_exp_f32_e32 v141, v141
	v_mul_f32_e32 v122, v122, v144
	v_mul_f32_e32 v123, v123, v145
	v_add_f32_e32 v141, 1.0, v141
	v_rcp_f32_e32 v162, v141
	v_mul_f32_e32 v141, 0xbfb8aa3b, v124
	v_exp_f32_e32 v141, v141
	s_nop 0
	v_add_f32_e32 v141, 1.0, v141
	v_rcp_f32_e32 v164, v141
	v_mul_f32_e32 v141, 0xbfb8aa3b, v129
	v_exp_f32_e32 v141, v141
	s_nop 0
	v_add_f32_e32 v141, 1.0, v141
	v_rcp_f32_e32 v163, v141
	v_mul_f32_e32 v141, 0xbfb8aa3b, v125
	v_exp_f32_e32 v141, v141
	v_mul_f32_e32 v128, v128, v162
	v_mul_f32_e32 v129, v129, v163
	v_add_f32_e32 v141, 1.0, v141
	v_rcp_f32_e32 v165, v141
	s_nop 0
	v_mul_f32_e32 v124, v124, v164
	v_mul_f32_e32 v125, v125, v165
.LBB0_380:
	v_mad_u64_u32 v[144:145], s[48:49], s82, v140, 0
	v_readlane_b32 s48, v232, 2
	s_waitcnt lgkmcnt(0)
	v_lshl_or_b32 v142, s69, 7, v148
	v_add3_u32 v145, v145, v150, v151
	v_readlane_b32 s49, v232, 3
	v_ashrrev_i32_e32 v143, 31, v142
	v_mul_f32_e32 v120, v120, v128
	v_mul_f32_e32 v121, v121, v129
	v_lshl_add_u64 v[144:145], v[144:145], 1, s[48:49]
	s_lshl_b64 s[48:49], s[82:83], 5
	v_mul_f32_e32 v118, v118, v126
	v_mul_f32_e32 v119, v119, v127
	v_mul_f32_e32 v124, v116, v124
	v_mul_f32_e32 v125, v117, v125
	v_mul_f32_e32 v116, v114, v122
	v_mul_f32_e32 v117, v115, v123
	v_lshl_add_u64 v[144:145], v[142:143], 1, v[144:145]
	v_cvt_pk_bf16_f32 v114, v118, v119
	v_cvt_pk_bf16_f32 v115, v120, v121
	v_cvt_pk_bf16_f32 v116, v116, v117
	v_cvt_pk_bf16_f32 v117, v124, v125
	s_and_b64 vcc, exec, s[42:43]
	global_store_dwordx4 v[144:145], v[114:117], off
	s_cbranch_vccnz .LBB0_382
	s_nop 0
	v_mul_f32_e32 v115, 0xbfb8aa3b, v106
	v_exp_f32_e32 v115, v115
	v_mul_f32_e32 v114, 0xbfb8aa3b, v110
	v_exp_f32_e32 v114, v114
	v_mul_f32_e32 v119, 0xbfb8aa3b, v108
	v_add_f32_e32 v115, 1.0, v115
	v_rcp_f32_e32 v116, v115
	v_mul_f32_e32 v115, 0xbfb8aa3b, v111
	v_exp_f32_e32 v115, v115
	v_add_f32_e32 v114, 1.0, v114
	v_exp_f32_e32 v119, v119
	v_rcp_f32_e32 v114, v114
	v_add_f32_e32 v115, 1.0, v115
	v_rcp_f32_e32 v115, v115
	v_add_f32_e32 v119, 1.0, v119
	v_mul_f32_e32 v117, 0xbfb8aa3b, v107
	v_mul_f32_e32 v118, 0xbfb8aa3b, v112
	v_rcp_f32_e32 v120, v119
	v_mul_f32_e32 v119, 0xbfb8aa3b, v113
	v_mul_f32_e32 v110, v110, v114
	v_mul_f32_e32 v111, v111, v115
	v_mul_f32_e32 v114, 0xbfb8aa3b, v109
	v_exp_f32_e32 v117, v117
	v_exp_f32_e32 v118, v118
	v_exp_f32_e32 v119, v119
	v_exp_f32_e32 v114, v114
	v_add_f32_e32 v117, 1.0, v117
	v_add_f32_e32 v118, 1.0, v118
	v_add_f32_e32 v119, 1.0, v119
	v_add_f32_e32 v114, 1.0, v114
	v_rcp_f32_e32 v117, v117
	v_rcp_f32_e32 v118, v118
	v_rcp_f32_e32 v119, v119
	v_rcp_f32_e32 v121, v114
	v_mul_f32_e32 v106, v106, v116
	v_mul_f32_e32 v107, v107, v117
	v_mul_f32_e32 v112, v112, v118
	v_mul_f32_e32 v113, v113, v119
	v_mul_f32_e32 v108, v108, v120
	v_mul_f32_e32 v109, v109, v121
.LBB0_382:
	s_nop 0
	v_mul_f32_e32 v104, v104, v112
	v_mul_f32_e32 v105, v105, v113
	v_mul_f32_e32 v102, v102, v110
	v_mul_f32_e32 v103, v103, v111
	v_mul_f32_e32 v108, v100, v108
	v_mul_f32_e32 v109, v101, v109
	v_mul_f32_e32 v100, v98, v106
	v_mul_f32_e32 v101, v99, v107
	v_lshl_add_u64 v[114:115], s[48:49], 0, v[144:145]
	v_cvt_pk_bf16_f32 v98, v102, v103
	v_cvt_pk_bf16_f32 v99, v104, v105
	v_cvt_pk_bf16_f32 v100, v100, v101
	v_cvt_pk_bf16_f32 v101, v108, v109
	s_and_b64 vcc, exec, s[42:43]
	global_store_dwordx4 v[114:115], v[98:101], off
	s_cbranch_vccnz .LBB0_384
	s_nop 0
	v_mul_f32_e32 v99, 0xbfb8aa3b, v88
	v_exp_f32_e32 v99, v99
	v_mul_f32_e32 v98, 0xbfb8aa3b, v92
	v_exp_f32_e32 v98, v98
	v_mul_f32_e32 v103, 0xbfb8aa3b, v90
	v_add_f32_e32 v99, 1.0, v99
	v_rcp_f32_e32 v100, v99
	v_mul_f32_e32 v99, 0xbfb8aa3b, v93
	v_exp_f32_e32 v99, v99
	v_add_f32_e32 v98, 1.0, v98
	v_exp_f32_e32 v103, v103
	v_rcp_f32_e32 v98, v98
	v_add_f32_e32 v99, 1.0, v99
	v_rcp_f32_e32 v99, v99
	v_add_f32_e32 v103, 1.0, v103
	v_mul_f32_e32 v101, 0xbfb8aa3b, v89
	v_mul_f32_e32 v102, 0xbfb8aa3b, v94
	v_rcp_f32_e32 v104, v103
	v_mul_f32_e32 v103, 0xbfb8aa3b, v95
	v_mul_f32_e32 v92, v92, v98
	v_mul_f32_e32 v93, v93, v99
	v_mul_f32_e32 v98, 0xbfb8aa3b, v91
	v_exp_f32_e32 v101, v101
	v_exp_f32_e32 v102, v102
	v_exp_f32_e32 v103, v103
	v_exp_f32_e32 v98, v98
	v_add_f32_e32 v101, 1.0, v101
	v_add_f32_e32 v102, 1.0, v102
	v_add_f32_e32 v103, 1.0, v103
	v_add_f32_e32 v98, 1.0, v98
	v_rcp_f32_e32 v101, v101
	v_rcp_f32_e32 v102, v102
	v_rcp_f32_e32 v103, v103
	v_rcp_f32_e32 v105, v98
	v_mul_f32_e32 v88, v88, v100
	v_mul_f32_e32 v89, v89, v101
	v_mul_f32_e32 v94, v94, v102
	v_mul_f32_e32 v95, v95, v103
	v_mul_f32_e32 v90, v90, v104
	v_mul_f32_e32 v91, v91, v105

.Lal_p1:
	s_nop 0
	v_mul_f32_e32 v86, v86, v94
	v_mul_f32_e32 v87, v87, v95
	v_mul_f32_e32 v84, v84, v92
	v_mul_f32_e32 v85, v85, v93
	v_mul_f32_e32 v90, v82, v90
	v_mul_f32_e32 v91, v83, v91
	v_mul_f32_e32 v82, v80, v88
	v_mul_f32_e32 v83, v81, v89
	v_lshl_add_u64 v[98:99], s[48:49], 1, v[144:145]
	v_cvt_pk_bf16_f32 v80, v84, v85
	v_cvt_pk_bf16_f32 v81, v86, v87
	v_cvt_pk_bf16_f32 v82, v82, v83
	v_cvt_pk_bf16_f32 v83, v90, v91
	s_and_b64 vcc, exec, s[42:43]
	global_store_dwordx4 v[98:99], v[80:83], off
	s_cbranch_vccnz .LBB0_386
	s_nop 0
	v_mul_f32_e32 v81, 0xbfb8aa3b, v72
	v_exp_f32_e32 v81, v81
	v_mul_f32_e32 v80, 0xbfb8aa3b, v76
	v_exp_f32_e32 v80, v80
	v_mul_f32_e32 v85, 0xbfb8aa3b, v74
	v_add_f32_e32 v81, 1.0, v81
	v_rcp_f32_e32 v82, v81
	v_mul_f32_e32 v81, 0xbfb8aa3b, v77
	v_exp_f32_e32 v81, v81
	v_add_f32_e32 v80, 1.0, v80
	v_exp_f32_e32 v85, v85
	v_rcp_f32_e32 v80, v80
	v_add_f32_e32 v81, 1.0, v81
	v_rcp_f32_e32 v81, v81
	v_add_f32_e32 v85, 1.0, v85
	v_mul_f32_e32 v83, 0xbfb8aa3b, v73
	v_mul_f32_e32 v84, 0xbfb8aa3b, v78
	v_rcp_f32_e32 v86, v85
	v_mul_f32_e32 v85, 0xbfb8aa3b, v79
	v_mul_f32_e32 v76, v76, v80
	v_mul_f32_e32 v77, v77, v81
	v_mul_f32_e32 v80, 0xbfb8aa3b, v75
	v_exp_f32_e32 v83, v83
	v_exp_f32_e32 v84, v84
	v_exp_f32_e32 v85, v85
	v_exp_f32_e32 v80, v80
	v_add_f32_e32 v83, 1.0, v83
	v_add_f32_e32 v84, 1.0, v84
	v_add_f32_e32 v85, 1.0, v85
	v_add_f32_e32 v80, 1.0, v80
	v_rcp_f32_e32 v83, v83
	v_rcp_f32_e32 v84, v84
	v_rcp_f32_e32 v85, v85
	v_rcp_f32_e32 v87, v80
	v_mul_f32_e32 v72, v72, v82
	v_mul_f32_e32 v73, v73, v83
	v_mul_f32_e32 v78, v78, v84
	v_mul_f32_e32 v79, v79, v85
	v_mul_f32_e32 v74, v74, v86
	v_mul_f32_e32 v75, v75, v87
.LBB0_386:
	s_nop 0
	v_mul_f32_e32 v70, v70, v78
	v_mul_f32_e32 v71, v71, v79
	v_mul_f32_e32 v68, v68, v76
	v_mul_f32_e32 v69, v69, v77
	v_mul_f32_e32 v74, v66, v74
	v_mul_f32_e32 v75, v67, v75
	v_mul_f32_e32 v66, v64, v72
	v_mul_f32_e32 v67, v65, v73
	v_lshl_add_u64 v[80:81], s[48:49], 0, v[98:99]
	v_cvt_pk_bf16_f32 v64, v68, v69
	v_cvt_pk_bf16_f32 v65, v70, v71
	v_cvt_pk_bf16_f32 v66, v66, v67
	v_cvt_pk_bf16_f32 v67, v74, v75
	s_and_b64 vcc, exec, s[42:43]
	global_store_dwordx4 v[80:81], v[64:67], off
	s_cbranch_vccnz .LBB0_388
	s_nop 0
	v_mul_f32_e32 v65, 0xbfb8aa3b, v56
	v_exp_f32_e32 v65, v65
	v_mul_f32_e32 v64, 0xbfb8aa3b, v60
	v_exp_f32_e32 v64, v64
	v_mul_f32_e32 v69, 0xbfb8aa3b, v58
	v_add_f32_e32 v65, 1.0, v65
	v_rcp_f32_e32 v66, v65
	v_mul_f32_e32 v65, 0xbfb8aa3b, v61
	v_exp_f32_e32 v65, v65
	v_add_f32_e32 v64, 1.0, v64
	v_exp_f32_e32 v69, v69
	v_rcp_f32_e32 v64, v64
	v_add_f32_e32 v65, 1.0, v65
	v_rcp_f32_e32 v65, v65
	v_add_f32_e32 v69, 1.0, v69
	v_mul_f32_e32 v67, 0xbfb8aa3b, v57
	v_mul_f32_e32 v68, 0xbfb8aa3b, v62
	v_rcp_f32_e32 v70, v69
	v_mul_f32_e32 v69, 0xbfb8aa3b, v63
	v_mul_f32_e32 v60, v60, v64
	v_mul_f32_e32 v61, v61, v65
	v_mul_f32_e32 v64, 0xbfb8aa3b, v59
	v_exp_f32_e32 v67, v67
	v_exp_f32_e32 v68, v68
	v_exp_f32_e32 v69, v69
	v_exp_f32_e32 v64, v64
	v_add_f32_e32 v67, 1.0, v67
	v_add_f32_e32 v68, 1.0, v68
	v_add_f32_e32 v69, 1.0, v69
	v_add_f32_e32 v64, 1.0, v64
	v_rcp_f32_e32 v67, v67
	v_rcp_f32_e32 v68, v68
	v_rcp_f32_e32 v69, v69
	v_rcp_f32_e32 v71, v64
	v_mul_f32_e32 v56, v56, v66
	v_mul_f32_e32 v57, v57, v67
	v_mul_f32_e32 v62, v62, v68
	v_mul_f32_e32 v63, v63, v69
	v_mul_f32_e32 v58, v58, v70
	v_mul_f32_e32 v59, v59, v71
.LBB0_388:
	s_nop 0
	v_mul_f32_e32 v54, v54, v62
	v_mul_f32_e32 v55, v55, v63
	v_mul_f32_e32 v52, v52, v60
	v_mul_f32_e32 v53, v53, v61
	v_mul_f32_e32 v58, v50, v58
	v_mul_f32_e32 v59, v51, v59
	v_mul_f32_e32 v50, v48, v56
	v_mul_f32_e32 v51, v49, v57
	v_lshl_add_u64 v[64:65], s[48:49], 3, v[144:145]
	v_cvt_pk_bf16_f32 v48, v52, v53
	v_cvt_pk_bf16_f32 v49, v54, v55
	v_cvt_pk_bf16_f32 v50, v50, v51
	v_cvt_pk_bf16_f32 v51, v58, v59
	s_and_b64 vcc, exec, s[42:43]
	global_store_dwordx4 v[64:65], v[48:51], off
	s_cbranch_vccnz .LBB0_390
	s_nop 0
	v_mul_f32_e32 v49, 0xbfb8aa3b, v40
	v_exp_f32_e32 v49, v49
	v_mul_f32_e32 v48, 0xbfb8aa3b, v44
	v_exp_f32_e32 v48, v48
	v_mul_f32_e32 v53, 0xbfb8aa3b, v42
	v_add_f32_e32 v49, 1.0, v49
	v_rcp_f32_e32 v50, v49
	v_mul_f32_e32 v49, 0xbfb8aa3b, v45
	v_exp_f32_e32 v49, v49
	v_add_f32_e32 v48, 1.0, v48
	v_exp_f32_e32 v53, v53
	v_rcp_f32_e32 v48, v48
	v_add_f32_e32 v49, 1.0, v49
	v_rcp_f32_e32 v49, v49
	v_add_f32_e32 v53, 1.0, v53
	v_mul_f32_e32 v51, 0xbfb8aa3b, v41
	v_mul_f32_e32 v52, 0xbfb8aa3b, v46
	v_rcp_f32_e32 v54, v53
	v_mul_f32_e32 v53, 0xbfb8aa3b, v47
	v_mul_f32_e32 v44, v44, v48
	v_mul_f32_e32 v45, v45, v49
	v_mul_f32_e32 v48, 0xbfb8aa3b, v43
	v_exp_f32_e32 v51, v51
	v_exp_f32_e32 v52, v52
	v_exp_f32_e32 v53, v53
	v_exp_f32_e32 v48, v48
	v_add_f32_e32 v51, 1.0, v51
	v_add_f32_e32 v52, 1.0, v52
	v_add_f32_e32 v53, 1.0, v53
	v_add_f32_e32 v48, 1.0, v48
	v_rcp_f32_e32 v51, v51
	v_rcp_f32_e32 v52, v52
	v_rcp_f32_e32 v53, v53
	v_rcp_f32_e32 v55, v48
	v_mul_f32_e32 v40, v40, v50
	v_mul_f32_e32 v41, v41, v51
	v_mul_f32_e32 v46, v46, v52
	v_mul_f32_e32 v47, v47, v53
	v_mul_f32_e32 v42, v42, v54
	v_mul_f32_e32 v43, v43, v55
.LBB0_390:
	s_nop 0
	v_mul_f32_e32 v38, v38, v46
	v_mul_f32_e32 v39, v39, v47
	v_mul_f32_e32 v36, v36, v44
	v_mul_f32_e32 v37, v37, v45
	v_mul_f32_e32 v42, v34, v42
	v_mul_f32_e32 v43, v35, v43
	v_mul_f32_e32 v34, v32, v40
	v_mul_f32_e32 v35, v33, v41
	v_lshl_add_u64 v[48:49], s[48:49], 0, v[64:65]
	v_cvt_pk_bf16_f32 v32, v36, v37
	v_cvt_pk_bf16_f32 v33, v38, v39
	v_cvt_pk_bf16_f32 v34, v34, v35
	v_cvt_pk_bf16_f32 v35, v42, v43
	s_and_b64 vcc, exec, s[42:43]
	global_store_dwordx4 v[48:49], v[32:35], off
	s_cbranch_vccnz .LBB0_392
	s_nop 0
	v_mul_f32_e32 v33, 0xbfb8aa3b, v24
	v_exp_f32_e32 v33, v33
	v_mul_f32_e32 v32, 0xbfb8aa3b, v28
	v_exp_f32_e32 v32, v32
	v_mul_f32_e32 v37, 0xbfb8aa3b, v26
	v_add_f32_e32 v33, 1.0, v33
	v_rcp_f32_e32 v34, v33
	v_mul_f32_e32 v33, 0xbfb8aa3b, v29
	v_exp_f32_e32 v33, v33
	v_add_f32_e32 v32, 1.0, v32
	v_exp_f32_e32 v37, v37
	v_rcp_f32_e32 v32, v32
	v_add_f32_e32 v33, 1.0, v33
	v_rcp_f32_e32 v33, v33
	v_add_f32_e32 v37, 1.0, v37
	v_mul_f32_e32 v35, 0xbfb8aa3b, v25
	v_mul_f32_e32 v36, 0xbfb8aa3b, v30
	v_rcp_f32_e32 v38, v37
	v_mul_f32_e32 v37, 0xbfb8aa3b, v31
	v_mul_f32_e32 v28, v28, v32
	v_mul_f32_e32 v29, v29, v33
	v_mul_f32_e32 v32, 0xbfb8aa3b, v27
	v_exp_f32_e32 v35, v35
	v_exp_f32_e32 v36, v36
	v_exp_f32_e32 v37, v37
	v_exp_f32_e32 v32, v32
	v_add_f32_e32 v35, 1.0, v35
	v_add_f32_e32 v36, 1.0, v36
	v_add_f32_e32 v37, 1.0, v37
	v_add_f32_e32 v32, 1.0, v32
	v_rcp_f32_e32 v35, v35
	v_rcp_f32_e32 v36, v36
	v_rcp_f32_e32 v37, v37
	v_rcp_f32_e32 v39, v32
	v_mul_f32_e32 v24, v24, v34
	v_mul_f32_e32 v25, v25, v35
	v_mul_f32_e32 v30, v30, v36
	v_mul_f32_e32 v31, v31, v37
	v_mul_f32_e32 v26, v26, v38
	v_mul_f32_e32 v27, v27, v39
.LBB0_392:
	s_nop 0
	v_mul_f32_e32 v22, v22, v30
	v_mul_f32_e32 v23, v23, v31
	v_mul_f32_e32 v20, v20, v28
	v_mul_f32_e32 v21, v21, v29
	v_mul_f32_e32 v26, v18, v26
	v_mul_f32_e32 v27, v19, v27
	v_mul_f32_e32 v18, v16, v24
	v_mul_f32_e32 v19, v17, v25
	v_lshl_add_u64 v[32:33], s[48:49], 1, v[64:65]
	v_cvt_pk_bf16_f32 v16, v20, v21
	v_cvt_pk_bf16_f32 v17, v22, v23
	v_cvt_pk_bf16_f32 v18, v18, v19
	v_cvt_pk_bf16_f32 v19, v26, v27
	s_and_b64 vcc, exec, s[42:43]
	global_store_dwordx4 v[32:33], v[16:19], off
	s_cbranch_vccnz .LBB0_394
	s_nop 0
	v_mul_f32_e32 v17, 0xbfb8aa3b, v8
	v_exp_f32_e32 v17, v17
	v_mul_f32_e32 v16, 0xbfb8aa3b, v12
	v_exp_f32_e32 v16, v16
	v_mul_f32_e32 v21, 0xbfb8aa3b, v10
	v_add_f32_e32 v17, 1.0, v17
	v_rcp_f32_e32 v18, v17
	v_mul_f32_e32 v17, 0xbfb8aa3b, v13
	v_exp_f32_e32 v17, v17
	v_add_f32_e32 v16, 1.0, v16
	v_exp_f32_e32 v21, v21
	v_rcp_f32_e32 v16, v16
	v_add_f32_e32 v17, 1.0, v17
	v_rcp_f32_e32 v17, v17
	v_add_f32_e32 v21, 1.0, v21
	v_mul_f32_e32 v19, 0xbfb8aa3b, v9
	v_mul_f32_e32 v20, 0xbfb8aa3b, v14
	v_rcp_f32_e32 v22, v21
	v_mul_f32_e32 v21, 0xbfb8aa3b, v15
	v_mul_f32_e32 v12, v12, v16
	v_mul_f32_e32 v13, v13, v17
	v_mul_f32_e32 v16, 0xbfb8aa3b, v11
	v_exp_f32_e32 v19, v19
	v_exp_f32_e32 v20, v20
	v_exp_f32_e32 v21, v21
	v_exp_f32_e32 v16, v16
	v_add_f32_e32 v19, 1.0, v19
	v_add_f32_e32 v20, 1.0, v20
	v_add_f32_e32 v21, 1.0, v21
	v_add_f32_e32 v16, 1.0, v16
	v_rcp_f32_e32 v19, v19
	v_rcp_f32_e32 v20, v20
	v_rcp_f32_e32 v21, v21
	v_rcp_f32_e32 v23, v16
	v_mul_f32_e32 v8, v8, v18
	v_mul_f32_e32 v9, v9, v19
	v_mul_f32_e32 v14, v14, v20
	v_mul_f32_e32 v15, v15, v21
	v_mul_f32_e32 v10, v10, v22
	v_mul_f32_e32 v11, v11, v23
.LBB0_394:
	s_nop 0
	v_mul_f32_e32 v6, v6, v14
	v_mul_f32_e32 v7, v7, v15
	v_mul_f32_e32 v4, v4, v12
	v_mul_f32_e32 v5, v5, v13
	v_mul_f32_e32 v10, v2, v10
	v_mul_f32_e32 v11, v3, v11
	v_mul_f32_e32 v2, v0, v8
	v_mul_f32_e32 v3, v1, v9
	v_lshl_add_u64 v[16:17], s[48:49], 0, v[32:33]
	v_cvt_pk_bf16_f32 v0, v4, v5
	v_cvt_pk_bf16_f32 v1, v6, v7
	v_cvt_pk_bf16_f32 v2, v2, v3
	v_cvt_pk_bf16_f32 v3, v10, v11
	global_store_dwordx4 v[16:17], v[0:3], off
	s_and_b64 vcc, exec, s[40:41]
	s_mov_b64 s[40:41], -1
	s_cbranch_vccnz .LBB0_325
